# accumulator clears use 64-bit moves (half the instructions per tile)
# baseline (speedup 1.0000x reference)
.LBB0_46:
	s_ashr_i32 s49, s48, 31
	s_lshl_b64 s[22:23], s[48:49], 19
	v_cmp_lt_i64_e32 vcc, s[52:53], v[164:165]
	s_add_u32 s52, s96, s22
	s_addc_u32 s53, s97, s23
	s_and_b64 s[22:23], vcc, exec
	s_cselect_b32 s21, s53, s29
	s_cselect_b32 s34, s52, s28
	s_ashr_i32 s47, s46, 31
	s_lshl_b64 s[22:23], s[46:47], 19
	s_add_u32 s54, s16, s22
	s_addc_u32 s55, s17, s23
	s_and_b64 s[22:23], vcc, exec
	s_cselect_b32 s47, s55, s31
	s_cselect_b32 s49, s54, s30
	s_add_u32 s28, s28, 0x40080
	s_addc_u32 s29, s29, 0
	s_add_u32 s67, s30, 0x100
	v_mov_b32_e32 v2, 0
	s_addc_u32 s68, s31, 0
	s_mov_b32 s69, -2
	s_waitcnt lgkmcnt(0)
	v_mov_b32_e32 v3, v2
	v_mov_b64_e32 v[4:5], 0
	v_mov_b64_e32 v[6:7], 0
	v_mov_b64_e32 v[8:9], 0
	v_mov_b64_e32 v[18:19], 0
	v_mov_b64_e32 v[20:21], 0
	v_mov_b64_e32 v[22:23], 0
	v_mov_b64_e32 v[24:25], 0
	v_mov_b64_e32 v[34:35], 0
	v_mov_b64_e32 v[36:37], 0
	v_mov_b64_e32 v[38:39], 0
	v_mov_b64_e32 v[40:41], 0
	v_mov_b64_e32 v[50:51], 0
	v_mov_b64_e32 v[52:53], 0
	v_mov_b64_e32 v[54:55], 0
	v_mov_b64_e32 v[56:57], 0
	v_mov_b64_e32 v[10:11], 0
	v_mov_b64_e32 v[12:13], 0
	v_mov_b64_e32 v[14:15], 0
	v_mov_b64_e32 v[16:17], 0
	v_mov_b64_e32 v[26:27], 0
	v_mov_b64_e32 v[28:29], 0
	v_mov_b64_e32 v[30:31], 0
	v_mov_b64_e32 v[32:33], 0
	v_mov_b64_e32 v[42:43], 0
	v_mov_b64_e32 v[44:45], 0
	v_mov_b64_e32 v[46:47], 0
	v_mov_b64_e32 v[48:49], 0
	v_mov_b64_e32 v[58:59], 0
	v_mov_b64_e32 v[60:61], 0
	v_mov_b64_e32 v[62:63], 0
	v_mov_b64_e32 v[64:65], 0
	v_mov_b64_e32 v[66:67], 0
	v_mov_b64_e32 v[68:69], 0
	v_mov_b64_e32 v[70:71], 0
	v_mov_b64_e32 v[72:73], 0
	v_mov_b64_e32 v[82:83], 0
	v_mov_b64_e32 v[84:85], 0
	v_mov_b64_e32 v[86:87], 0
	v_mov_b64_e32 v[88:89], 0
	v_mov_b64_e32 v[98:99], 0
	v_mov_b64_e32 v[100:101], 0
	v_mov_b64_e32 v[102:103], 0
	v_mov_b64_e32 v[104:105], 0
	v_mov_b64_e32 v[114:115], 0
	v_mov_b64_e32 v[116:117], 0
	v_mov_b64_e32 v[118:119], 0
	v_mov_b64_e32 v[120:121], 0
	v_mov_b64_e32 v[74:75], 0
	v_mov_b64_e32 v[76:77], 0
	v_mov_b64_e32 v[78:79], 0
	v_mov_b64_e32 v[80:81], 0
	v_mov_b64_e32 v[90:91], 0
	v_mov_b64_e32 v[92:93], 0
	v_mov_b64_e32 v[94:95], 0
	v_mov_b64_e32 v[96:97], 0
	v_mov_b64_e32 v[106:107], 0
	v_mov_b64_e32 v[108:109], 0
	v_mov_b64_e32 v[110:111], 0
	v_mov_b64_e32 v[112:113], 0
	v_mov_b64_e32 v[122:123], 0
	v_mov_b64_e32 v[124:125], 0
	v_mov_b64_e32 v[126:127], 0
	v_mov_b64_e32 v[128:129], 0
	s_cmpk_gt_u32 s0, 0xff
	s_cbranch_scc0 .Lrs_i1_pre
	s_barrier

.LBB0_82:
	s_ashr_i32 s27, s26, 31
	v_mov_b64_e32 v[2:3], 0xb00
	s_lshl_b64 s[22:23], s[26:27], 19
	v_cmp_lt_i64_e32 vcc, s[36:37], v[2:3]
	s_add_u32 s36, s96, s22
	s_addc_u32 s37, s97, s23
	s_and_b64 s[22:23], vcc, exec
	s_cselect_b32 s27, s37, s29
	s_cselect_b32 s56, s36, s28
	s_ashr_i32 s7, s6, 31
	s_lshl_b64 s[22:23], s[6:7], 19
	s_add_u32 s44, s4, s22
	s_addc_u32 s45, s16, s23
	s_and_b64 s[22:23], vcc, exec
	s_cselect_b32 s7, s45, s31
	s_cselect_b32 s57, s44, s30
	s_add_u32 s28, s28, 0x40080
	s_addc_u32 s29, s29, 0
	s_add_u32 s58, s30, 0x100
	v_mov_b32_e32 v2, 0
	s_addc_u32 s59, s31, 0
	s_mov_b32 s60, -2
	v_mov_b32_e32 v3, v2
	v_mov_b64_e32 v[4:5], 0
	v_mov_b64_e32 v[10:11], 0
	v_mov_b64_e32 v[12:13], 0
	v_mov_b64_e32 v[18:19], 0
	v_mov_b64_e32 v[20:21], 0
	v_mov_b64_e32 v[26:27], 0
	v_mov_b64_e32 v[28:29], 0
	v_mov_b64_e32 v[34:35], 0
	v_mov_b64_e32 v[36:37], 0
	v_mov_b64_e32 v[42:43], 0
	v_mov_b64_e32 v[44:45], 0
	v_mov_b64_e32 v[50:51], 0
	v_mov_b64_e32 v[52:53], 0
	v_mov_b64_e32 v[58:59], 0
	v_mov_b64_e32 v[60:61], 0
	v_mov_b64_e32 v[6:7], 0
	v_mov_b64_e32 v[8:9], 0
	v_mov_b64_e32 v[14:15], 0
	v_mov_b64_e32 v[16:17], 0
	v_mov_b64_e32 v[22:23], 0
	v_mov_b64_e32 v[24:25], 0
	v_mov_b64_e32 v[30:31], 0
	v_mov_b64_e32 v[32:33], 0
	v_mov_b64_e32 v[38:39], 0
	v_mov_b64_e32 v[40:41], 0
	v_mov_b64_e32 v[46:47], 0
	v_mov_b64_e32 v[48:49], 0
	v_mov_b64_e32 v[54:55], 0
	v_mov_b64_e32 v[56:57], 0
	v_mov_b64_e32 v[62:63], 0
	v_mov_b64_e32 v[64:65], 0
	v_mov_b64_e32 v[66:67], 0
	v_mov_b64_e32 v[68:69], 0
	v_mov_b64_e32 v[74:75], 0
	v_mov_b64_e32 v[76:77], 0
	v_mov_b64_e32 v[82:83], 0
	v_mov_b64_e32 v[84:85], 0
	v_mov_b64_e32 v[90:91], 0
	v_mov_b64_e32 v[92:93], 0
	v_mov_b64_e32 v[98:99], 0
	v_mov_b64_e32 v[100:101], 0
	v_mov_b64_e32 v[106:107], 0
	v_mov_b64_e32 v[108:109], 0
	v_mov_b64_e32 v[114:115], 0
	v_mov_b64_e32 v[116:117], 0
	v_mov_b64_e32 v[122:123], 0
	v_mov_b64_e32 v[124:125], 0
	v_mov_b64_e32 v[70:71], 0
	v_mov_b64_e32 v[72:73], 0
	v_mov_b64_e32 v[78:79], 0
	v_mov_b64_e32 v[80:81], 0
	v_mov_b64_e32 v[86:87], 0
	v_mov_b64_e32 v[88:89], 0
	v_mov_b64_e32 v[94:95], 0
	v_mov_b64_e32 v[96:97], 0
	v_mov_b64_e32 v[102:103], 0
	v_mov_b64_e32 v[104:105], 0
	v_mov_b64_e32 v[110:111], 0
	v_mov_b64_e32 v[112:113], 0
	v_mov_b64_e32 v[118:119], 0
	v_mov_b64_e32 v[120:121], 0
	v_mov_b64_e32 v[126:127], 0
	v_mov_b64_e32 v[128:129], 0
	s_cmpk_gt_u32 s0, 0xff
	s_cbranch_scc0 .Lrs_i2_pre
	s_barrier

.LBB0_119:
	s_add_u32 s36, s36, 0x80
	s_addc_u32 s37, s37, 0
	s_add_u32 s48, s30, 0x100
	v_mov_b32_e32 v2, 0
	s_addc_u32 s49, s31, 0
	s_mov_b32 s22, 0
	s_waitcnt lgkmcnt(0)
	v_mov_b32_e32 v3, v2
	v_mov_b64_e32 v[4:5], 0
	v_mov_b64_e32 v[6:7], 0
	v_mov_b64_e32 v[8:9], 0
	v_mov_b64_e32 v[18:19], 0
	v_mov_b64_e32 v[20:21], 0
	v_mov_b64_e32 v[22:23], 0
	v_mov_b64_e32 v[24:25], 0
	v_mov_b64_e32 v[34:35], 0
	v_mov_b64_e32 v[36:37], 0
	v_mov_b64_e32 v[38:39], 0
	v_mov_b64_e32 v[40:41], 0
	v_mov_b64_e32 v[50:51], 0
	v_mov_b64_e32 v[52:53], 0
	v_mov_b64_e32 v[54:55], 0
	v_mov_b64_e32 v[56:57], 0
	v_mov_b64_e32 v[10:11], 0
	v_mov_b64_e32 v[12:13], 0
	v_mov_b64_e32 v[14:15], 0
	v_mov_b64_e32 v[16:17], 0
	v_mov_b64_e32 v[26:27], 0
	v_mov_b64_e32 v[28:29], 0
	v_mov_b64_e32 v[30:31], 0
	v_mov_b64_e32 v[32:33], 0
	v_mov_b64_e32 v[42:43], 0
	v_mov_b64_e32 v[44:45], 0
	v_mov_b64_e32 v[46:47], 0
	v_mov_b64_e32 v[48:49], 0
	v_mov_b64_e32 v[58:59], 0
	v_mov_b64_e32 v[60:61], 0
	v_mov_b64_e32 v[62:63], 0
	v_mov_b64_e32 v[64:65], 0
	v_mov_b64_e32 v[66:67], 0
	v_mov_b64_e32 v[68:69], 0
	v_mov_b64_e32 v[70:71], 0
	v_mov_b64_e32 v[72:73], 0
	v_mov_b64_e32 v[82:83], 0
	v_mov_b64_e32 v[84:85], 0
	v_mov_b64_e32 v[86:87], 0
	v_mov_b64_e32 v[88:89], 0
	v_mov_b64_e32 v[98:99], 0
	v_mov_b64_e32 v[100:101], 0
	v_mov_b64_e32 v[102:103], 0
	v_mov_b64_e32 v[104:105], 0
	v_mov_b64_e32 v[114:115], 0
	v_mov_b64_e32 v[116:117], 0
	v_mov_b64_e32 v[118:119], 0
	v_mov_b64_e32 v[120:121], 0
	v_mov_b64_e32 v[74:75], 0
	v_mov_b64_e32 v[76:77], 0
	v_mov_b64_e32 v[78:79], 0
	v_mov_b64_e32 v[80:81], 0
	v_mov_b64_e32 v[90:91], 0
	v_mov_b64_e32 v[92:93], 0
	v_mov_b64_e32 v[94:95], 0
	v_mov_b64_e32 v[96:97], 0
	v_mov_b64_e32 v[106:107], 0
	v_mov_b64_e32 v[108:109], 0
	v_mov_b64_e32 v[110:111], 0
	v_mov_b64_e32 v[112:113], 0
	v_mov_b64_e32 v[122:123], 0
	v_mov_b64_e32 v[124:125], 0
	v_mov_b64_e32 v[126:127], 0
	v_mov_b64_e32 v[128:129], 0
	s_cmpk_gt_u32 s16, 0xff
	s_cbranch_scc0 .Lrs_i3_pre
	s_barrier

.LBB0_288:
	s_ashr_i32 s27, s26, 31
	s_lshl_b64 s[22:23], s[26:27], 19
	v_cmp_lt_i64_e32 vcc, s[28:29], v[170:171]
	s_add_u32 s28, s96, s22
	s_addc_u32 s29, s97, s23
	s_and_b64 s[22:23], vcc, exec
	s_cselect_b32 s27, s29, s43
	s_cselect_b32 s50, s28, s42
	s_ashr_i32 s7, s6, 31
	s_lshl_b64 s[22:23], s[6:7], 19
	s_add_u32 s36, s10, s22
	s_addc_u32 s37, s11, s23
	s_and_b64 s[22:23], vcc, exec
	s_cselect_b32 s7, s37, s31
	s_cselect_b32 s51, s36, s30
	s_add_u32 s42, s42, 0x40080
	s_addc_u32 s43, s43, 0
	s_add_u32 s52, s30, 0x100
	v_mov_b32_e32 v2, 0
	s_addc_u32 s53, s31, 0
	s_mov_b32 s54, -2
	v_mov_b32_e32 v3, v2
	v_mov_b64_e32 v[4:5], 0
	v_mov_b64_e32 v[6:7], 0
	v_mov_b64_e32 v[8:9], 0
	v_mov_b64_e32 v[10:11], 0
	v_mov_b64_e32 v[12:13], 0
	v_mov_b64_e32 v[18:19], 0
	v_mov_b64_e32 v[20:21], 0
	v_mov_b64_e32 v[26:27], 0
	v_mov_b64_e32 v[28:29], 0
	v_mov_b64_e32 v[34:35], 0
	v_mov_b64_e32 v[36:37], 0
	v_mov_b64_e32 v[42:43], 0
	v_mov_b64_e32 v[44:45], 0
	v_mov_b64_e32 v[50:51], 0
	v_mov_b64_e32 v[52:53], 0
	v_mov_b64_e32 v[14:15], 0
	v_mov_b64_e32 v[16:17], 0
	v_mov_b64_e32 v[22:23], 0
	v_mov_b64_e32 v[24:25], 0
	v_mov_b64_e32 v[30:31], 0
	v_mov_b64_e32 v[32:33], 0
	v_mov_b64_e32 v[38:39], 0
	v_mov_b64_e32 v[40:41], 0
	v_mov_b64_e32 v[46:47], 0
	v_mov_b64_e32 v[48:49], 0
	v_mov_b64_e32 v[54:55], 0
	v_mov_b64_e32 v[56:57], 0
	v_mov_b64_e32 v[58:59], 0
	v_mov_b64_e32 v[60:61], 0
	v_mov_b64_e32 v[62:63], 0
	v_mov_b64_e32 v[64:65], 0
	v_mov_b64_e32 v[66:67], 0
	v_mov_b64_e32 v[68:69], 0
	v_mov_b64_e32 v[70:71], 0
	v_mov_b64_e32 v[72:73], 0
	v_mov_b64_e32 v[74:75], 0
	v_mov_b64_e32 v[76:77], 0
	v_mov_b64_e32 v[82:83], 0
	v_mov_b64_e32 v[84:85], 0
	v_mov_b64_e32 v[90:91], 0
	v_mov_b64_e32 v[92:93], 0
	v_mov_b64_e32 v[98:99], 0
	v_mov_b64_e32 v[100:101], 0
	v_mov_b64_e32 v[106:107], 0
	v_mov_b64_e32 v[108:109], 0
	v_mov_b64_e32 v[114:115], 0
	v_mov_b64_e32 v[116:117], 0
	v_mov_b64_e32 v[78:79], 0
	v_mov_b64_e32 v[80:81], 0
	v_mov_b64_e32 v[86:87], 0
	v_mov_b64_e32 v[88:89], 0
	v_mov_b64_e32 v[94:95], 0
	v_mov_b64_e32 v[96:97], 0
	v_mov_b64_e32 v[102:103], 0
	v_mov_b64_e32 v[104:105], 0
	v_mov_b64_e32 v[110:111], 0
	v_mov_b64_e32 v[112:113], 0
	v_mov_b64_e32 v[118:119], 0
	v_mov_b64_e32 v[120:121], 0
	v_mov_b64_e32 v[122:123], 0
	v_mov_b64_e32 v[124:125], 0
	v_mov_b64_e32 v[126:127], 0
	v_mov_b64_e32 v[128:129], 0
	s_cmpk_gt_u32 s0, 0xff
	s_cbranch_scc0 .Lrs_proj0_pre
	s_barrier

.LBB0_361:
	s_ashr_i32 s25, s24, 31
	s_lshl_b64 s[20:21], s[24:25], 19
	v_cmp_lt_i64_e32 vcc, s[26:27], v[174:175]
	s_add_u32 s26, s46, s20
	s_addc_u32 s27, s47, s21
	s_and_b64 s[20:21], vcc, exec
	s_cselect_b32 s17, s27, s29
	s_cselect_b32 s20, s26, s28
	s_ashr_i32 s9, s8, 31
	s_lshl_b64 s[22:23], s[8:9], 19
	v_readlane_b32 s36, v254, 42
	v_readlane_b32 s37, v254, 43
	s_add_u32 s36, s36, s22
	s_addc_u32 s37, s37, s23
	s_and_b64 s[22:23], vcc, exec
	s_cselect_b32 s9, s37, s31
	s_cselect_b32 s21, s36, s30
	s_add_u32 s28, s28, 0x40080
	s_addc_u32 s29, s29, 0
	s_add_u32 s25, s30, 0x100
	v_mov_b32_e32 v2, 0
	s_addc_u32 s34, s31, 0
	s_mov_b32 s44, -2
	v_mov_b32_e32 v3, v2
	v_mov_b64_e32 v[4:5], 0
	v_mov_b64_e32 v[6:7], 0
	v_mov_b64_e32 v[8:9], 0
	v_mov_b64_e32 v[18:19], 0
	v_mov_b64_e32 v[20:21], 0
	v_mov_b64_e32 v[22:23], 0
	v_mov_b64_e32 v[24:25], 0
	v_mov_b64_e32 v[34:35], 0
	v_mov_b64_e32 v[36:37], 0
	v_mov_b64_e32 v[38:39], 0
	v_mov_b64_e32 v[40:41], 0
	v_mov_b64_e32 v[50:51], 0
	v_mov_b64_e32 v[52:53], 0
	v_mov_b64_e32 v[54:55], 0
	v_mov_b64_e32 v[56:57], 0
	v_mov_b64_e32 v[10:11], 0
	v_mov_b64_e32 v[12:13], 0
	v_mov_b64_e32 v[14:15], 0
	v_mov_b64_e32 v[16:17], 0
	v_mov_b64_e32 v[26:27], 0
	v_mov_b64_e32 v[28:29], 0
	v_mov_b64_e32 v[30:31], 0
	v_mov_b64_e32 v[32:33], 0
	v_mov_b64_e32 v[42:43], 0
	v_mov_b64_e32 v[44:45], 0
	v_mov_b64_e32 v[46:47], 0
	v_mov_b64_e32 v[48:49], 0
	v_mov_b64_e32 v[58:59], 0
	v_mov_b64_e32 v[60:61], 0
	v_mov_b64_e32 v[62:63], 0
	v_mov_b64_e32 v[64:65], 0
	v_mov_b64_e32 v[66:67], 0
	v_mov_b64_e32 v[68:69], 0
	v_mov_b64_e32 v[70:71], 0
	v_mov_b64_e32 v[72:73], 0
	v_mov_b64_e32 v[82:83], 0
	v_mov_b64_e32 v[84:85], 0
	v_mov_b64_e32 v[86:87], 0
	v_mov_b64_e32 v[88:89], 0
	v_mov_b64_e32 v[98:99], 0
	v_mov_b64_e32 v[100:101], 0
	v_mov_b64_e32 v[102:103], 0
	v_mov_b64_e32 v[104:105], 0
	v_mov_b64_e32 v[114:115], 0
	v_mov_b64_e32 v[116:117], 0
	v_mov_b64_e32 v[118:119], 0
	v_mov_b64_e32 v[120:121], 0
	v_mov_b64_e32 v[74:75], 0
	v_mov_b64_e32 v[76:77], 0
	v_mov_b64_e32 v[78:79], 0
	v_mov_b64_e32 v[80:81], 0
	v_mov_b64_e32 v[90:91], 0
	v_mov_b64_e32 v[92:93], 0
	v_mov_b64_e32 v[94:95], 0
	v_mov_b64_e32 v[96:97], 0
	v_mov_b64_e32 v[106:107], 0
	v_mov_b64_e32 v[108:109], 0
	v_mov_b64_e32 v[110:111], 0
	v_mov_b64_e32 v[112:113], 0
	v_mov_b64_e32 v[122:123], 0
	v_mov_b64_e32 v[124:125], 0
	v_mov_b64_e32 v[126:127], 0
	v_mov_b64_e32 v[128:129], 0
	s_cmpk_gt_u32 s4, 0xff
	s_cbranch_scc0 .Lrs_proj1_pre
	s_barrier
